# SGU phase: v-row loads issued together and the 16 per-row wave reductions batched
# speedup vs baseline: 1.0037x; 1.0037x over previous
.LBB0_249:
	s_and_b32 s1, s71, 0xffffff80
	s_and_b32 s73, s72, 3
	v_add_u32_e32 v55, s1, v107
	v_mov_b64_e32 v[58:59], s[42:43]
	v_mad_i64_i32 v[0:1], s[2:3], v55, s84, v[58:59]
	s_lshl_b32 s34, s73, 8
	v_lshl_add_u64 v[0:1], v[0:1], 0, s[34:35]
	v_lshl_add_u64 v[104:105], v[0:1], 0, v[176:177]
	v_or_b32_e32 v0, 1, v55
	v_mad_i64_i32 v[0:1], s[2:3], v0, s84, v[58:59]
	v_lshl_add_u64 v[0:1], v[0:1], 0, s[34:35]
	v_lshl_add_u64 v[102:103], v[0:1], 0, v[176:177]
	v_or_b32_e32 v0, 2, v55
	v_mad_i64_i32 v[0:1], s[2:3], v0, s84, v[58:59]
	v_lshl_add_u64 v[0:1], v[0:1], 0, s[34:35]
	v_lshl_add_u64 v[100:101], v[0:1], 0, v[176:177]
	v_or_b32_e32 v0, 3, v55
	v_mad_i64_i32 v[0:1], s[2:3], v0, s84, v[58:59]
	v_lshl_add_u64 v[0:1], v[0:1], 0, s[34:35]
	v_lshl_add_u64 v[32:33], v[0:1], 0, v[176:177]
	v_or_b32_e32 v0, 4, v55
	v_mad_i64_i32 v[0:1], s[2:3], v0, s84, v[58:59]
	v_lshl_add_u64 v[0:1], v[0:1], 0, s[34:35]
	v_lshl_add_u64 v[34:35], v[0:1], 0, v[176:177]
	v_or_b32_e32 v0, 5, v55
	v_mad_i64_i32 v[0:1], s[2:3], v0, s84, v[58:59]
	v_lshl_add_u64 v[0:1], v[0:1], 0, s[34:35]
	v_lshl_add_u64 v[36:37], v[0:1], 0, v[176:177]
	v_or_b32_e32 v0, 6, v55
	v_mad_i64_i32 v[0:1], s[2:3], v0, s84, v[58:59]
	v_lshl_add_u64 v[0:1], v[0:1], 0, s[34:35]
	v_lshl_add_u64 v[38:39], v[0:1], 0, v[176:177]
	v_or_b32_e32 v0, 7, v55
	v_mad_i64_i32 v[0:1], s[2:3], v0, s84, v[58:59]
	v_lshl_add_u64 v[0:1], v[0:1], 0, s[34:35]
	v_lshl_add_u64 v[40:41], v[0:1], 0, v[176:177]
	v_or_b32_e32 v0, 8, v55
	v_mad_i64_i32 v[0:1], s[2:3], v0, s84, v[58:59]
	v_lshl_add_u64 v[0:1], v[0:1], 0, s[34:35]
	v_lshl_add_u64 v[42:43], v[0:1], 0, v[176:177]
	v_or_b32_e32 v0, 9, v55
	v_mad_i64_i32 v[0:1], s[2:3], v0, s84, v[58:59]
	v_lshl_add_u64 v[0:1], v[0:1], 0, s[34:35]
	v_lshl_add_u64 v[44:45], v[0:1], 0, v[176:177]
	v_or_b32_e32 v0, 10, v55
	v_mad_i64_i32 v[0:1], s[2:3], v0, s84, v[58:59]
	v_lshl_add_u64 v[0:1], v[0:1], 0, s[34:35]
	v_lshl_add_u64 v[46:47], v[0:1], 0, v[176:177]
	v_or_b32_e32 v0, 11, v55
	v_mad_i64_i32 v[0:1], s[2:3], v0, s84, v[58:59]
	v_lshl_add_u64 v[0:1], v[0:1], 0, s[34:35]
	v_lshl_add_u64 v[90:91], v[0:1], 0, v[176:177]
	v_or_b32_e32 v0, 12, v55
	v_mad_i64_i32 v[0:1], s[2:3], v0, s84, v[58:59]
	v_lshl_add_u64 v[0:1], v[0:1], 0, s[34:35]
	v_lshl_add_u64 v[92:93], v[0:1], 0, v[176:177]
	v_or_b32_e32 v0, 13, v55
	v_mad_i64_i32 v[0:1], s[2:3], v0, s84, v[58:59]
	v_lshl_add_u64 v[0:1], v[0:1], 0, s[34:35]
	v_lshl_add_u64 v[94:95], v[0:1], 0, v[176:177]
	v_or_b32_e32 v0, 14, v55
	v_mad_i64_i32 v[0:1], s[2:3], v0, s84, v[58:59]
	v_lshl_add_u64 v[0:1], v[0:1], 0, s[34:35]
	v_lshl_add_u64 v[96:97], v[0:1], 0, v[176:177]
	v_or_b32_e32 v0, 15, v55
	s_lshl_b32 s1, s73, 7
	v_mad_i64_i32 v[0:1], s[2:3], v0, s84, v[58:59]
	v_lshl_add_u64 v[0:1], v[0:1], 0, s[34:35]
	s_or_b32 s2, s1, s70
	s_mov_b32 s3, s35
	v_or_b32_e32 v56, v55, v106
	v_lshl_add_u64 v[98:99], v[0:1], 0, v[176:177]
	v_lshl_add_u64 v[0:1], s[2:3], 2, v[52:53]
	v_lshl_add_u64 v[60:61], v[48:49], 0, s[2:3]
	v_mad_i64_i32 v[58:59], s[2:3], v56, s84, v[58:59]
	global_load_dword v119, v[0:1], off
	global_load_dword v118, v[0:1], off offset:256
	v_lshlrev_b64 v[0:1], 9, v[60:61]
	v_lshl_add_u64 v[58:59], v[58:59], 0, s[34:35]
	v_mov_b32_e32 v55, v177
	v_lshl_add_u64 v[4:5], v[50:51], 0, v[0:1]
	v_lshl_add_u64 v[60:61], v[60:61], 2, s[68:69]
	v_lshl_add_u64 v[58:59], v[58:59], 0, v[54:55]
	global_load_dwordx4 v[24:27], v[4:5], off offset:16
	global_load_dwordx4 v[28:31], v[4:5], off
	global_load_dwordx4 v[16:19], v[4:5], off offset:144
	global_load_dwordx4 v[20:23], v[4:5], off offset:128
	global_load_dwordx4 v[8:11], v[4:5], off offset:272
	global_load_dwordx4 v[12:15], v[4:5], off offset:256
	global_load_dwordx4 v[0:3], v[4:5], off offset:400
	s_nop 0
	global_load_dwordx4 v[4:7], v[4:5], off offset:384
	v_ashrrev_i32_e32 v57, 31, v56
	global_load_dword v117, v[60:61], off
	global_load_dwordx2 v[88:89], v[58:59], off
	global_load_dwordx2 v[86:87], v[58:59], off offset:2048
	global_load_dwordx2 v[84:85], v[58:59], off offset:32
	global_load_dwordx2 v[82:83], v[58:59], off offset:2080
	global_load_dwordx2 v[80:81], v[58:59], off offset:64
	global_load_dwordx2 v[78:79], v[58:59], off offset:2112
	global_load_dwordx2 v[76:77], v[58:59], off offset:96
	global_load_dwordx2 v[74:75], v[58:59], off offset:2144
	global_load_dwordx2 v[72:73], v[58:59], off offset:128
	global_load_dwordx2 v[70:71], v[58:59], off offset:2176
	global_load_dwordx2 v[68:69], v[58:59], off offset:160
	global_load_dwordx2 v[66:67], v[58:59], off offset:2208
	global_load_dwordx2 v[64:65], v[58:59], off offset:192
	global_load_dwordx2 v[62:63], v[58:59], off offset:2240
	global_load_dwordx2 v[60:61], v[58:59], off offset:224
	s_nop 0
	global_load_dwordx2 v[58:59], v[58:59], off offset:2272
	s_nop 0
	global_load_ushort v131, v[104:105], off offset:1024
	global_load_ushort v132, v[104:105], off offset:1152
	global_load_ushort v129, v[102:103], off offset:1024
	global_load_ushort v133, v[102:103], off offset:1152
	global_load_ushort v128, v[100:101], off offset:1024
	global_load_ushort v130, v[100:101], off offset:1152
	global_load_ushort v126, v[32:33], off offset:1024
	global_load_ushort v127, v[32:33], off offset:1152
	global_load_ushort v124, v[34:35], off offset:1024
	global_load_ushort v125, v[34:35], off offset:1152
	global_load_ushort v122, v[36:37], off offset:1024
	global_load_ushort v123, v[36:37], off offset:1152
	global_load_ushort v120, v[38:39], off offset:1024
	global_load_ushort v121, v[38:39], off offset:1152
	global_load_ushort v103, v[40:41], off offset:1024
	global_load_ushort v104, v[40:41], off offset:1152
	global_load_ushort v101, v[42:43], off offset:1024
	global_load_ushort v102, v[42:43], off offset:1152
	global_load_ushort v100, v[44:45], off offset:1024
	global_load_ushort v44, v[44:45], off offset:1152
	global_load_ushort v42, v[46:47], off offset:1024
	global_load_ushort v43, v[46:47], off offset:1152
	global_load_ushort v40, v[90:91], off offset:1024
	global_load_ushort v41, v[90:91], off offset:1152
	global_load_ushort v38, v[92:93], off offset:1024
	global_load_ushort v39, v[92:93], off offset:1152
	global_load_ushort v36, v[94:95], off offset:1024
	global_load_ushort v37, v[94:95], off offset:1152
	global_load_ushort v34, v[96:97], off offset:1024
	global_load_ushort v35, v[96:97], off offset:1152
	global_load_ushort v32, v[98:99], off offset:1024
	global_load_ushort v33, v[98:99], off offset:1152
	s_mov_b64 s[2:3], 0xd800800
	s_mov_b32 s1, 0xd800000
	s_waitcnt vmcnt(0)
	v_lshlrev_b32_e32 v131, 16, v131
	v_lshlrev_b32_e32 v132, 16, v132
	v_lshlrev_b32_e32 v129, 16, v129
	v_lshlrev_b32_e32 v133, 16, v133
	v_lshlrev_b32_e32 v128, 16, v128
	v_lshlrev_b32_e32 v130, 16, v130
	v_lshlrev_b32_e32 v126, 16, v126
	v_lshlrev_b32_e32 v127, 16, v127
	v_lshlrev_b32_e32 v124, 16, v124
	v_lshlrev_b32_e32 v125, 16, v125
	v_lshlrev_b32_e32 v122, 16, v122
	v_lshlrev_b32_e32 v123, 16, v123
	v_lshlrev_b32_e32 v120, 16, v120
	v_lshlrev_b32_e32 v121, 16, v121
	v_lshlrev_b32_e32 v103, 16, v103
	v_lshlrev_b32_e32 v104, 16, v104
	v_lshlrev_b32_e32 v101, 16, v101
	v_lshlrev_b32_e32 v102, 16, v102
	v_lshlrev_b32_e32 v100, 16, v100
	v_lshlrev_b32_e32 v44, 16, v44
	v_lshlrev_b32_e32 v42, 16, v42
	v_lshlrev_b32_e32 v43, 16, v43
	v_lshlrev_b32_e32 v40, 16, v40
	v_lshlrev_b32_e32 v41, 16, v41
	v_lshlrev_b32_e32 v38, 16, v38
	v_lshlrev_b32_e32 v39, 16, v39
	v_lshlrev_b32_e32 v36, 16, v36
	v_lshlrev_b32_e32 v37, 16, v37
	v_lshlrev_b32_e32 v34, 16, v34
	v_lshlrev_b32_e32 v35, 16, v35
	v_lshlrev_b32_e32 v32, 16, v32
	v_lshlrev_b32_e32 v33, 16, v33
	v_mul_f32_e32 v200, v131, v131
	v_mul_f32_e32 v216, v132, v132
	v_mul_f32_e32 v201, v129, v129
	v_mul_f32_e32 v217, v133, v133
	v_mul_f32_e32 v202, v128, v128
	v_mul_f32_e32 v218, v130, v130
	v_mul_f32_e32 v203, v126, v126
	v_mul_f32_e32 v219, v127, v127
	v_mul_f32_e32 v204, v124, v124
	v_mul_f32_e32 v220, v125, v125
	v_mul_f32_e32 v205, v122, v122
	v_mul_f32_e32 v221, v123, v123
	v_mul_f32_e32 v206, v120, v120
	v_mul_f32_e32 v222, v121, v121
	v_mul_f32_e32 v207, v103, v103
	v_mul_f32_e32 v223, v104, v104
	v_mul_f32_e32 v208, v101, v101
	v_mul_f32_e32 v224, v102, v102
	v_mul_f32_e32 v209, v100, v100
	v_mul_f32_e32 v225, v44, v44
	v_mul_f32_e32 v210, v42, v42
	v_mul_f32_e32 v226, v43, v43
	v_mul_f32_e32 v211, v40, v40
	v_mul_f32_e32 v227, v41, v41
	v_mul_f32_e32 v212, v38, v38
	v_mul_f32_e32 v228, v39, v39
	v_mul_f32_e32 v213, v36, v36
	v_mul_f32_e32 v229, v37, v37
	v_mul_f32_e32 v214, v34, v34
	v_mul_f32_e32 v230, v35, v35
	v_mul_f32_e32 v215, v32, v32
	v_mul_f32_e32 v231, v33, v33
	v_add_f32_e32 v200, v200, v216
	v_add_f32_e32 v201, v201, v217
	v_add_f32_e32 v202, v202, v218
	v_add_f32_e32 v203, v203, v219
	v_add_f32_e32 v204, v204, v220
	v_add_f32_e32 v205, v205, v221
	v_add_f32_e32 v206, v206, v222
	v_add_f32_e32 v207, v207, v223
	v_add_f32_e32 v208, v208, v224
	v_add_f32_e32 v209, v209, v225
	v_add_f32_e32 v210, v210, v226
	v_add_f32_e32 v211, v211, v227
	v_add_f32_e32 v212, v212, v228
	v_add_f32_e32 v213, v213, v229
	v_add_f32_e32 v214, v214, v230
	v_add_f32_e32 v215, v215, v231
	ds_bpermute_b32 v216, v108, v200
	ds_bpermute_b32 v217, v108, v201
	ds_bpermute_b32 v218, v108, v202
	ds_bpermute_b32 v219, v108, v203
	ds_bpermute_b32 v220, v108, v204
	ds_bpermute_b32 v221, v108, v205
	ds_bpermute_b32 v222, v108, v206
	ds_bpermute_b32 v223, v108, v207
	ds_bpermute_b32 v224, v108, v208
	ds_bpermute_b32 v225, v108, v209
	ds_bpermute_b32 v226, v108, v210
	ds_bpermute_b32 v227, v108, v211
	ds_bpermute_b32 v228, v108, v212
	ds_bpermute_b32 v229, v108, v213
	ds_bpermute_b32 v230, v108, v214
	ds_bpermute_b32 v231, v108, v215
	s_waitcnt lgkmcnt(0)
	v_add_f32_e32 v200, v200, v216
	v_add_f32_e32 v201, v201, v217
	v_add_f32_e32 v202, v202, v218
	v_add_f32_e32 v203, v203, v219
	v_add_f32_e32 v204, v204, v220
	v_add_f32_e32 v205, v205, v221
	v_add_f32_e32 v206, v206, v222
	v_add_f32_e32 v207, v207, v223
	v_add_f32_e32 v208, v208, v224
	v_add_f32_e32 v209, v209, v225
	v_add_f32_e32 v210, v210, v226
	v_add_f32_e32 v211, v211, v227
	v_add_f32_e32 v212, v212, v228
	v_add_f32_e32 v213, v213, v229
	v_add_f32_e32 v214, v214, v230
	v_add_f32_e32 v215, v215, v231
	ds_bpermute_b32 v216, v109, v200
	ds_bpermute_b32 v217, v109, v201
	ds_bpermute_b32 v218, v109, v202
	ds_bpermute_b32 v219, v109, v203
	ds_bpermute_b32 v220, v109, v204
	ds_bpermute_b32 v221, v109, v205
	ds_bpermute_b32 v222, v109, v206
	ds_bpermute_b32 v223, v109, v207
	ds_bpermute_b32 v224, v109, v208
	ds_bpermute_b32 v225, v109, v209
	ds_bpermute_b32 v226, v109, v210
	ds_bpermute_b32 v227, v109, v211
	ds_bpermute_b32 v228, v109, v212
	ds_bpermute_b32 v229, v109, v213
	ds_bpermute_b32 v230, v109, v214
	ds_bpermute_b32 v231, v109, v215
	s_waitcnt lgkmcnt(0)
	v_add_f32_e32 v200, v200, v216
	v_add_f32_e32 v201, v201, v217
	v_add_f32_e32 v202, v202, v218
	v_add_f32_e32 v203, v203, v219
	v_add_f32_e32 v204, v204, v220
	v_add_f32_e32 v205, v205, v221
	v_add_f32_e32 v206, v206, v222
	v_add_f32_e32 v207, v207, v223
	v_add_f32_e32 v208, v208, v224
	v_add_f32_e32 v209, v209, v225
	v_add_f32_e32 v210, v210, v226
	v_add_f32_e32 v211, v211, v227
	v_add_f32_e32 v212, v212, v228
	v_add_f32_e32 v213, v213, v229
	v_add_f32_e32 v214, v214, v230
	v_add_f32_e32 v215, v215, v231
	ds_bpermute_b32 v216, v110, v200
	ds_bpermute_b32 v217, v110, v201
	ds_bpermute_b32 v218, v110, v202
	ds_bpermute_b32 v219, v110, v203
	ds_bpermute_b32 v220, v110, v204
	ds_bpermute_b32 v221, v110, v205
	ds_bpermute_b32 v222, v110, v206
	ds_bpermute_b32 v223, v110, v207
	ds_bpermute_b32 v224, v110, v208
	ds_bpermute_b32 v225, v110, v209
	ds_bpermute_b32 v226, v110, v210
	ds_bpermute_b32 v227, v110, v211
	ds_bpermute_b32 v228, v110, v212
	ds_bpermute_b32 v229, v110, v213
	ds_bpermute_b32 v230, v110, v214
	ds_bpermute_b32 v231, v110, v215
	s_waitcnt lgkmcnt(0)
	v_add_f32_e32 v200, v200, v216
	v_add_f32_e32 v201, v201, v217
	v_add_f32_e32 v202, v202, v218
	v_add_f32_e32 v203, v203, v219
	v_add_f32_e32 v204, v204, v220
	v_add_f32_e32 v205, v205, v221
	v_add_f32_e32 v206, v206, v222
	v_add_f32_e32 v207, v207, v223
	v_add_f32_e32 v208, v208, v224
	v_add_f32_e32 v209, v209, v225
	v_add_f32_e32 v210, v210, v226
	v_add_f32_e32 v211, v211, v227
	v_add_f32_e32 v212, v212, v228
	v_add_f32_e32 v213, v213, v229
	v_add_f32_e32 v214, v214, v230
	v_add_f32_e32 v215, v215, v231
	ds_bpermute_b32 v216, v111, v200
	ds_bpermute_b32 v217, v111, v201
	ds_bpermute_b32 v218, v111, v202
	ds_bpermute_b32 v219, v111, v203
	ds_bpermute_b32 v220, v111, v204
	ds_bpermute_b32 v221, v111, v205
	ds_bpermute_b32 v222, v111, v206
	ds_bpermute_b32 v223, v111, v207
	ds_bpermute_b32 v224, v111, v208
	ds_bpermute_b32 v225, v111, v209
	ds_bpermute_b32 v226, v111, v210
	ds_bpermute_b32 v227, v111, v211
	ds_bpermute_b32 v228, v111, v212
	ds_bpermute_b32 v229, v111, v213
	ds_bpermute_b32 v230, v111, v214
	ds_bpermute_b32 v231, v111, v215
	s_waitcnt lgkmcnt(0)
	v_add_f32_e32 v200, v200, v216
	v_add_f32_e32 v201, v201, v217
	v_add_f32_e32 v202, v202, v218
	v_add_f32_e32 v203, v203, v219
	v_add_f32_e32 v204, v204, v220
	v_add_f32_e32 v205, v205, v221
	v_add_f32_e32 v206, v206, v222
	v_add_f32_e32 v207, v207, v223
	v_add_f32_e32 v208, v208, v224
	v_add_f32_e32 v209, v209, v225
	v_add_f32_e32 v210, v210, v226
	v_add_f32_e32 v211, v211, v227
	v_add_f32_e32 v212, v212, v228
	v_add_f32_e32 v213, v213, v229
	v_add_f32_e32 v214, v214, v230
	v_add_f32_e32 v215, v215, v231
	ds_bpermute_b32 v216, v112, v200
	ds_bpermute_b32 v217, v112, v201
	ds_bpermute_b32 v218, v112, v202
	ds_bpermute_b32 v219, v112, v203
	ds_bpermute_b32 v220, v112, v204
	ds_bpermute_b32 v221, v112, v205
	ds_bpermute_b32 v222, v112, v206
	ds_bpermute_b32 v223, v112, v207
	ds_bpermute_b32 v224, v112, v208
	ds_bpermute_b32 v225, v112, v209
	ds_bpermute_b32 v226, v112, v210
	ds_bpermute_b32 v227, v112, v211
	ds_bpermute_b32 v228, v112, v212
	ds_bpermute_b32 v229, v112, v213
	ds_bpermute_b32 v230, v112, v214
	ds_bpermute_b32 v231, v112, v215
	s_waitcnt lgkmcnt(0)
	v_add_f32_e32 v200, v200, v216
	v_add_f32_e32 v201, v201, v217
	v_add_f32_e32 v202, v202, v218
	v_add_f32_e32 v203, v203, v219
	v_add_f32_e32 v204, v204, v220
	v_add_f32_e32 v205, v205, v221
	v_add_f32_e32 v206, v206, v222
	v_add_f32_e32 v207, v207, v223
	v_add_f32_e32 v208, v208, v224
	v_add_f32_e32 v209, v209, v225
	v_add_f32_e32 v210, v210, v226
	v_add_f32_e32 v211, v211, v227
	v_add_f32_e32 v212, v212, v228
	v_add_f32_e32 v213, v213, v229
	v_add_f32_e32 v214, v214, v230
	v_add_f32_e32 v215, v215, v231
	ds_bpermute_b32 v216, v113, v200
	ds_bpermute_b32 v217, v113, v201
	ds_bpermute_b32 v218, v113, v202
	ds_bpermute_b32 v219, v113, v203
	ds_bpermute_b32 v220, v113, v204
	ds_bpermute_b32 v221, v113, v205
	ds_bpermute_b32 v222, v113, v206
	ds_bpermute_b32 v223, v113, v207
	ds_bpermute_b32 v224, v113, v208
	ds_bpermute_b32 v225, v113, v209
	ds_bpermute_b32 v226, v113, v210
	ds_bpermute_b32 v227, v113, v211
	ds_bpermute_b32 v228, v113, v212
	ds_bpermute_b32 v229, v113, v213
	ds_bpermute_b32 v230, v113, v214
	ds_bpermute_b32 v231, v113, v215
	s_waitcnt lgkmcnt(0)
	v_add_f32_e32 v200, v200, v216
	v_add_f32_e32 v201, v201, v217
	v_add_f32_e32 v202, v202, v218
	v_add_f32_e32 v203, v203, v219
	v_add_f32_e32 v204, v204, v220
	v_add_f32_e32 v205, v205, v221
	v_add_f32_e32 v206, v206, v222
	v_add_f32_e32 v207, v207, v223
	v_add_f32_e32 v208, v208, v224
	v_add_f32_e32 v209, v209, v225
	v_add_f32_e32 v210, v210, v226
	v_add_f32_e32 v211, v211, v227
	v_add_f32_e32 v212, v212, v228
	v_add_f32_e32 v213, v213, v229
	v_add_f32_e32 v214, v214, v230
	v_add_f32_e32 v215, v215, v231
	v_fmamk_f32 v200, v200, 0x3c000000, v189
	v_fmamk_f32 v201, v201, 0x3c000000, v189
	v_fmamk_f32 v202, v202, 0x3c000000, v189
	v_fmamk_f32 v203, v203, 0x3c000000, v189
	v_fmamk_f32 v204, v204, 0x3c000000, v189
	v_fmamk_f32 v205, v205, 0x3c000000, v189
	v_fmamk_f32 v206, v206, 0x3c000000, v189
	v_fmamk_f32 v207, v207, 0x3c000000, v189
	v_fmamk_f32 v208, v208, 0x3c000000, v189
	v_fmamk_f32 v209, v209, 0x3c000000, v189
	v_fmamk_f32 v210, v210, 0x3c000000, v189
	v_fmamk_f32 v211, v211, 0x3c000000, v189
	v_fmamk_f32 v212, v212, 0x3c000000, v189
	v_fmamk_f32 v213, v213, 0x3c000000, v189
	v_fmamk_f32 v214, v214, 0x3c000000, v189
	v_fmamk_f32 v215, v215, 0x3c000000, v189
	v_rsq_f32_e32 v200, v200
	v_rsq_f32_e32 v201, v201
	v_rsq_f32_e32 v202, v202
	v_rsq_f32_e32 v203, v203
	v_rsq_f32_e32 v204, v204
	v_rsq_f32_e32 v205, v205
	v_rsq_f32_e32 v206, v206
	v_rsq_f32_e32 v207, v207
	v_rsq_f32_e32 v208, v208
	v_rsq_f32_e32 v209, v209
	v_rsq_f32_e32 v210, v210
	v_rsq_f32_e32 v211, v211
	v_rsq_f32_e32 v212, v212
	v_rsq_f32_e32 v213, v213
	v_rsq_f32_e32 v214, v214
	v_rsq_f32_e32 v215, v215
	v_mul_f32_e32 v131, v200, v131
	v_mul_f32_e32 v132, v200, v132
	v_mul_f32_e32 v131, v119, v131
	v_mul_f32_e32 v132, v118, v132
	v_cvt_pk_bf16_f32 v131, v131, v177
	v_cvt_pk_bf16_f32 v132, v132, v177
	ds_write_b16 v115, v131
	ds_write_b16 v115, v132 offset:16896
	v_mul_f32_e32 v129, v201, v129
	v_mul_f32_e32 v133, v201, v133
	v_mul_f32_e32 v129, v119, v129
	v_mul_f32_e32 v133, v118, v133
	v_cvt_pk_bf16_f32 v129, v129, v177
	v_cvt_pk_bf16_f32 v133, v133, v177
	ds_write_b16 v115, v129 offset:2
	ds_write_b16 v115, v133 offset:16898
	v_mul_f32_e32 v128, v202, v128
	v_mul_f32_e32 v130, v202, v130
	v_mul_f32_e32 v128, v119, v128
	v_mul_f32_e32 v130, v118, v130
	v_cvt_pk_bf16_f32 v128, v128, v177
	v_cvt_pk_bf16_f32 v130, v130, v177
	ds_write_b16 v115, v128 offset:4
	ds_write_b16 v115, v130 offset:16900
	v_mul_f32_e32 v126, v203, v126
	v_mul_f32_e32 v127, v203, v127
	v_mul_f32_e32 v126, v119, v126
	v_mul_f32_e32 v127, v118, v127
	v_cvt_pk_bf16_f32 v126, v126, v177
	v_cvt_pk_bf16_f32 v127, v127, v177
	ds_write_b16 v115, v126 offset:6
	ds_write_b16 v115, v127 offset:16902
	v_mul_f32_e32 v124, v204, v124
	v_mul_f32_e32 v125, v204, v125
	v_mul_f32_e32 v124, v119, v124
	v_mul_f32_e32 v125, v118, v125
	v_cvt_pk_bf16_f32 v124, v124, v177
	v_cvt_pk_bf16_f32 v125, v125, v177
	ds_write_b16 v115, v124 offset:8
	ds_write_b16 v115, v125 offset:16904
	v_mul_f32_e32 v122, v205, v122
	v_mul_f32_e32 v123, v205, v123
	v_mul_f32_e32 v122, v119, v122
	v_mul_f32_e32 v123, v118, v123
	v_cvt_pk_bf16_f32 v122, v122, v177
	v_cvt_pk_bf16_f32 v123, v123, v177
	ds_write_b16 v115, v122 offset:10
	ds_write_b16 v115, v123 offset:16906
	v_mul_f32_e32 v120, v206, v120
	v_mul_f32_e32 v121, v206, v121
	v_mul_f32_e32 v120, v119, v120
	v_mul_f32_e32 v121, v118, v121
	v_cvt_pk_bf16_f32 v120, v120, v177
	v_cvt_pk_bf16_f32 v121, v121, v177
	ds_write_b16 v115, v120 offset:12
	ds_write_b16 v115, v121 offset:16908
	v_mul_f32_e32 v103, v207, v103
	v_mul_f32_e32 v104, v207, v104
	v_mul_f32_e32 v103, v119, v103
	v_mul_f32_e32 v104, v118, v104
	v_cvt_pk_bf16_f32 v103, v103, v177
	v_cvt_pk_bf16_f32 v104, v104, v177
	ds_write_b16 v115, v103 offset:14
	ds_write_b16 v115, v104 offset:16910
	v_mul_f32_e32 v101, v208, v101
	v_mul_f32_e32 v102, v208, v102
	v_mul_f32_e32 v101, v119, v101
	v_mul_f32_e32 v102, v118, v102
	v_cvt_pk_bf16_f32 v101, v101, v177
	v_cvt_pk_bf16_f32 v102, v102, v177
	ds_write_b16 v115, v101 offset:16
	ds_write_b16 v115, v102 offset:16912
	v_mul_f32_e32 v100, v209, v100
	v_mul_f32_e32 v44, v209, v44
	v_mul_f32_e32 v100, v119, v100
	v_mul_f32_e32 v44, v118, v44
	v_cvt_pk_bf16_f32 v100, v100, v177
	v_cvt_pk_bf16_f32 v44, v44, v177
	ds_write_b16 v115, v100 offset:18
	ds_write_b16 v115, v44 offset:16914
	v_mul_f32_e32 v42, v210, v42
	v_mul_f32_e32 v43, v210, v43
	v_mul_f32_e32 v42, v119, v42
	v_mul_f32_e32 v43, v118, v43
	v_cvt_pk_bf16_f32 v42, v42, v177
	v_cvt_pk_bf16_f32 v43, v43, v177
	ds_write_b16 v115, v42 offset:20
	ds_write_b16 v115, v43 offset:16916
	v_mul_f32_e32 v40, v211, v40
	v_mul_f32_e32 v41, v211, v41
	v_mul_f32_e32 v40, v119, v40
	v_mul_f32_e32 v41, v118, v41
	v_cvt_pk_bf16_f32 v40, v40, v177
	v_cvt_pk_bf16_f32 v41, v41, v177
	ds_write_b16 v115, v40 offset:22
	ds_write_b16 v115, v41 offset:16918
	v_mul_f32_e32 v38, v212, v38
	v_mul_f32_e32 v39, v212, v39
	v_mul_f32_e32 v38, v119, v38
	v_mul_f32_e32 v39, v118, v39
	v_cvt_pk_bf16_f32 v38, v38, v177
	v_cvt_pk_bf16_f32 v39, v39, v177
	ds_write_b16 v115, v38 offset:24
	ds_write_b16 v115, v39 offset:16920
	v_mul_f32_e32 v36, v213, v36
	v_mul_f32_e32 v37, v213, v37
	v_mul_f32_e32 v36, v119, v36
	v_mul_f32_e32 v37, v118, v37
	v_cvt_pk_bf16_f32 v36, v36, v177
	v_cvt_pk_bf16_f32 v37, v37, v177
	ds_write_b16 v115, v36 offset:26
	ds_write_b16 v115, v37 offset:16922
	v_mul_f32_e32 v34, v214, v34
	v_mul_f32_e32 v35, v214, v35
	v_mul_f32_e32 v34, v119, v34
	v_mul_f32_e32 v35, v118, v35
	v_cvt_pk_bf16_f32 v34, v34, v177
	v_cvt_pk_bf16_f32 v35, v35, v177
	ds_write_b16 v115, v34 offset:28
	ds_write_b16 v115, v35 offset:16924
	v_mul_f32_e32 v32, v215, v32
	v_mul_f32_e32 v33, v215, v33
	v_mul_f32_e32 v32, v119, v32
	v_mul_f32_e32 v33, v118, v33
	v_cvt_pk_bf16_f32 v32, v32, v177
	v_cvt_pk_bf16_f32 v33, v33, v177
	ds_write_b16 v116, v32
	ds_write_b16 v116, v33 offset:16896
	s_waitcnt lgkmcnt(0)
	s_barrier
	v_cvt_pk_bf16_f32 v44, v28, v29
	v_cvt_pk_bf16_f32 v45, v30, v31
	v_cvt_pk_bf16_f32 v46, v24, v25
	v_cvt_pk_bf16_f32 v47, v26, v27
	v_cvt_pk_bf16_f32 v40, v20, v21
	v_cvt_pk_bf16_f32 v41, v22, v23
	v_cvt_pk_bf16_f32 v42, v16, v17
	v_cvt_pk_bf16_f32 v43, v18, v19
	v_cvt_pk_bf16_f32 v36, v12, v13
	v_cvt_pk_bf16_f32 v37, v14, v15
	v_cvt_pk_bf16_f32 v38, v8, v9
	v_cvt_pk_bf16_f32 v39, v10, v11
	v_cvt_pk_bf16_f32 v32, v4, v5
	v_cvt_pk_bf16_f32 v33, v6, v7
	v_cvt_pk_bf16_f32 v34, v0, v1
	v_cvt_pk_bf16_f32 v35, v2, v3
	ds_read2_b64 v[0:3], v114 offset1:1
	ds_read2_b64 v[4:7], v114 offset0:8 offset1:9
	s_waitcnt lgkmcnt(1)
	v_mfma_f32_16x16x32_bf16 v[0:3], v[0:3], v[44:47], 0
	s_waitcnt lgkmcnt(0)
	v_mfma_f32_16x16x32_bf16 v[0:3], v[4:7], v[40:43], v[0:3]
	ds_read2_b64 v[4:7], v114 offset0:16 offset1:17
	s_waitcnt lgkmcnt(0)
	v_mfma_f32_16x16x32_bf16 v[0:3], v[4:7], v[36:39], v[0:3]
	ds_read2_b64 v[4:7], v114 offset0:24 offset1:25
	s_waitcnt lgkmcnt(0)
	v_mfma_f32_16x16x32_bf16 v[28:31], v[4:7], v[32:35], v[0:3]
	s_nop 4
	v_add_u32_e32 v0, 0x1080, v114
	ds_read2_b64 v[0:3], v0 offset1:1
	v_add_u32_e32 v4, 0x10c0, v114
	ds_read2_b64 v[4:7], v4 offset1:1
	s_waitcnt lgkmcnt(1)
	v_mfma_f32_16x16x32_bf16 v[0:3], v[0:3], v[44:47], 0
	v_add_f32_e32 v28, v117, v28
	v_add_f32_e32 v29, v117, v29
	v_add_f32_e32 v30, v117, v30
	s_waitcnt lgkmcnt(0)
	v_mfma_f32_16x16x32_bf16 v[0:3], v[4:7], v[40:43], v[0:3]
	v_add_u32_e32 v4, 0x1100, v114
	ds_read2_b64 v[4:7], v4 offset1:1
	v_add_f32_e32 v31, v117, v31
	s_waitcnt lgkmcnt(0)
	v_mfma_f32_16x16x32_bf16 v[0:3], v[4:7], v[36:39], v[0:3]
	v_add_u32_e32 v4, 0x1140, v114
	ds_read2_b64 v[4:7], v4 offset1:1
	s_waitcnt lgkmcnt(0)
	v_mfma_f32_16x16x32_bf16 v[24:27], v[4:7], v[32:35], v[0:3]
	s_nop 3
	v_add_u32_e32 v0, 0x2100, v114
	ds_read2_b64 v[0:3], v0 offset1:1
	v_add_u32_e32 v4, 0x2140, v114
	ds_read2_b64 v[4:7], v4 offset1:1
	s_waitcnt lgkmcnt(1)
	v_mfma_f32_16x16x32_bf16 v[0:3], v[0:3], v[44:47], 0
	v_add_f32_e32 v24, v117, v24
	v_add_f32_e32 v25, v117, v25
	v_add_f32_e32 v26, v117, v26
	s_waitcnt lgkmcnt(0)
	v_mfma_f32_16x16x32_bf16 v[0:3], v[4:7], v[40:43], v[0:3]
	v_add_u32_e32 v4, 0x2180, v114
	ds_read2_b64 v[4:7], v4 offset1:1
	v_add_f32_e32 v27, v117, v27
	s_waitcnt lgkmcnt(0)
	v_mfma_f32_16x16x32_bf16 v[0:3], v[4:7], v[36:39], v[0:3]
	v_add_u32_e32 v4, 0x21c0, v114
	ds_read2_b64 v[4:7], v4 offset1:1
	s_waitcnt lgkmcnt(0)
	v_mfma_f32_16x16x32_bf16 v[20:23], v[4:7], v[32:35], v[0:3]
	s_nop 3
	v_add_u32_e32 v0, 0x3180, v114
	ds_read2_b64 v[0:3], v0 offset1:1
	v_add_u32_e32 v4, 0x31c0, v114
	ds_read2_b64 v[4:7], v4 offset1:1
	s_waitcnt lgkmcnt(1)
	v_mfma_f32_16x16x32_bf16 v[0:3], v[0:3], v[44:47], 0
	v_add_f32_e32 v20, v117, v20
	v_add_f32_e32 v21, v117, v21
	v_add_f32_e32 v22, v117, v22
	s_waitcnt lgkmcnt(0)
	v_mfma_f32_16x16x32_bf16 v[0:3], v[4:7], v[40:43], v[0:3]
	v_add_u32_e32 v4, 0x3200, v114
	ds_read2_b64 v[4:7], v4 offset1:1
	v_add_f32_e32 v23, v117, v23
	s_waitcnt lgkmcnt(0)
	v_mfma_f32_16x16x32_bf16 v[0:3], v[4:7], v[36:39], v[0:3]
	v_add_u32_e32 v4, 0x3240, v114
	ds_read2_b64 v[4:7], v4 offset1:1
	s_waitcnt lgkmcnt(0)
	v_mfma_f32_16x16x32_bf16 v[16:19], v[4:7], v[32:35], v[0:3]
	s_nop 3
	v_add_u32_e32 v0, 0x4200, v114
	ds_read2_b64 v[0:3], v0 offset1:1
	v_add_u32_e32 v4, 0x4240, v114
	ds_read2_b64 v[4:7], v4 offset1:1
	s_waitcnt lgkmcnt(1)
	v_mfma_f32_16x16x32_bf16 v[0:3], v[0:3], v[44:47], 0
	v_add_f32_e32 v16, v117, v16
	v_add_f32_e32 v17, v117, v17
	v_add_f32_e32 v18, v117, v18
	s_waitcnt lgkmcnt(0)
	v_mfma_f32_16x16x32_bf16 v[0:3], v[4:7], v[40:43], v[0:3]
	v_add_u32_e32 v4, 0x4280, v114
	ds_read2_b64 v[4:7], v4 offset1:1
	v_add_f32_e32 v19, v117, v19
	s_waitcnt lgkmcnt(0)
	v_mfma_f32_16x16x32_bf16 v[0:3], v[4:7], v[36:39], v[0:3]
	v_add_u32_e32 v4, 0x42c0, v114
	ds_read2_b64 v[4:7], v4 offset1:1
	s_waitcnt lgkmcnt(0)
	v_mfma_f32_16x16x32_bf16 v[12:15], v[4:7], v[32:35], v[0:3]
	s_nop 3
	v_add_u32_e32 v0, 0x5280, v114
	ds_read2_b64 v[0:3], v0 offset1:1
	v_add_u32_e32 v4, 0x52c0, v114
	ds_read2_b64 v[4:7], v4 offset1:1
	s_waitcnt lgkmcnt(1)
	v_mfma_f32_16x16x32_bf16 v[0:3], v[0:3], v[44:47], 0
	v_add_f32_e32 v12, v117, v12
	v_add_f32_e32 v13, v117, v13
	v_add_f32_e32 v14, v117, v14
	s_waitcnt lgkmcnt(0)
	v_mfma_f32_16x16x32_bf16 v[0:3], v[4:7], v[40:43], v[0:3]
	v_add_u32_e32 v4, 0x5300, v114
	ds_read2_b64 v[4:7], v4 offset1:1
	v_add_f32_e32 v15, v117, v15
	s_waitcnt lgkmcnt(0)
	v_mfma_f32_16x16x32_bf16 v[0:3], v[4:7], v[36:39], v[0:3]
	v_add_u32_e32 v4, 0x5340, v114
	ds_read2_b64 v[4:7], v4 offset1:1
	s_waitcnt lgkmcnt(0)
	v_mfma_f32_16x16x32_bf16 v[8:11], v[4:7], v[32:35], v[0:3]
	s_nop 3
	v_add_u32_e32 v0, 0x6300, v114
	ds_read2_b64 v[0:3], v0 offset1:1
	v_add_u32_e32 v4, 0x6340, v114
	ds_read2_b64 v[4:7], v4 offset1:1
	s_waitcnt lgkmcnt(1)
	v_mfma_f32_16x16x32_bf16 v[0:3], v[0:3], v[44:47], 0
	v_add_f32_e32 v8, v117, v8
	v_add_f32_e32 v9, v117, v9
	v_add_f32_e32 v10, v117, v10
	s_waitcnt lgkmcnt(0)
	v_mfma_f32_16x16x32_bf16 v[0:3], v[4:7], v[40:43], v[0:3]
	v_add_u32_e32 v4, 0x6380, v114
	ds_read2_b64 v[4:7], v4 offset1:1
	v_add_f32_e32 v11, v117, v11
	s_waitcnt lgkmcnt(0)
	v_mfma_f32_16x16x32_bf16 v[0:3], v[4:7], v[36:39], v[0:3]
	v_add_u32_e32 v4, 0x63c0, v114
	ds_read2_b64 v[4:7], v4 offset1:1
	s_waitcnt lgkmcnt(0)
	v_mfma_f32_16x16x32_bf16 v[4:7], v[4:7], v[32:35], v[0:3]
	s_nop 3
	v_add_u32_e32 v0, 0x7380, v114
	ds_read2_b64 v[0:3], v0 offset1:1
	s_nop 1
	v_add_f32_e32 v4, v117, v4
	s_waitcnt lgkmcnt(0)
	v_mfma_f32_16x16x32_bf16 v[0:3], v[0:3], v[44:47], 0
	v_add_u32_e32 v44, 0x73c0, v114
	ds_read2_b64 v[44:47], v44 offset1:1
	v_add_f32_e32 v5, v117, v5
	s_waitcnt lgkmcnt(0)
	v_mfma_f32_16x16x32_bf16 v[0:3], v[44:47], v[40:43], v[0:3]
	v_add_u32_e32 v40, 0x7400, v114
	ds_read2_b64 v[40:43], v40 offset1:1
	v_add_f32_e32 v6, v117, v6
	s_waitcnt lgkmcnt(0)
	v_mfma_f32_16x16x32_bf16 v[0:3], v[40:43], v[36:39], v[0:3]
	v_add_u32_e32 v36, 0x7440, v114
	ds_read2_b64 v[36:39], v36 offset1:1
	v_add_f32_e32 v7, v117, v7
	s_waitcnt lgkmcnt(0)
	v_mfma_f32_16x16x32_bf16 v[0:3], v[36:39], v[32:35], v[0:3]
	v_lshlrev_b32_e32 v36, 16, v88
	v_mul_f32_e32 v28, v28, v36
	v_lshlrev_b32_e32 v36, 16, v86
	v_mul_f32_e32 v37, 0xbfb8aa3b, v36
	v_exp_f32_e32 v37, v37
	v_lshlrev_b64 v[32:33], 12, v[56:57]
	v_lshl_add_u64 v[32:33], s[38:39], 0, v[32:33]
	v_lshl_add_u64 v[32:33], v[32:33], 0, s[34:35]
	v_lshl_add_u64 v[34:35], v[32:33], 0, v[54:55]
	v_add_f32_e32 v37, 1.0, v37
	v_lshl_add_u64 v[32:33], v[34:35], 0, s[2:3]
	v_div_scale_f32 v38, s[2:3], v37, v37, v36
	v_rcp_f32_e32 v39, v38
	v_add_f32_e32 v0, v117, v0
	v_add_f32_e32 v1, v117, v1
	v_add_f32_e32 v2, v117, v2
	v_fma_f32 v40, -v38, v39, 1.0
	v_fmac_f32_e32 v39, v40, v39
	v_div_scale_f32 v40, vcc, v36, v37, v36
	v_mul_f32_e32 v41, v40, v39
	v_fma_f32 v42, -v38, v41, v40
	v_fmac_f32_e32 v41, v42, v39
	v_fma_f32 v38, -v38, v41, v40
	v_div_fmas_f32 v38, v38, v39, v41
	v_div_fixup_f32 v36, v38, v37, v36
	v_mul_f32_e32 v28, v36, v28
	v_and_b32_e32 v36, 0xffff0000, v88
	v_mul_f32_e32 v29, v29, v36
	v_and_b32_e32 v36, 0xffff0000, v86
	v_mul_f32_e32 v37, 0xbfb8aa3b, v36
	v_exp_f32_e32 v37, v37
	v_add_f32_e32 v3, v117, v3
	v_add_f32_e32 v37, 1.0, v37
	v_div_scale_f32 v38, s[2:3], v37, v37, v36
	v_rcp_f32_e32 v39, v38
	s_nop 0
	v_fma_f32 v40, -v38, v39, 1.0
	v_fmac_f32_e32 v39, v40, v39
	v_div_scale_f32 v40, vcc, v36, v37, v36
	v_mul_f32_e32 v41, v40, v39
	v_fma_f32 v42, -v38, v41, v40
	v_fmac_f32_e32 v41, v42, v39
	v_fma_f32 v38, -v38, v41, v40
	v_div_fmas_f32 v38, v38, v39, v41
	v_div_fixup_f32 v36, v38, v37, v36
	v_mul_f32_e32 v29, v36, v29
	v_lshlrev_b32_e32 v36, 16, v89
	v_mul_f32_e32 v30, v30, v36
	v_lshlrev_b32_e32 v36, 16, v87
	v_mul_f32_e32 v37, 0xbfb8aa3b, v36
	v_exp_f32_e32 v37, v37
	s_nop 0
	v_add_f32_e32 v37, 1.0, v37
	v_div_scale_f32 v38, s[2:3], v37, v37, v36
	v_rcp_f32_e32 v39, v38
	s_nop 0
	v_fma_f32 v40, -v38, v39, 1.0
	v_fmac_f32_e32 v39, v40, v39
	v_div_scale_f32 v40, vcc, v36, v37, v36
	v_mul_f32_e32 v41, v40, v39
	v_fma_f32 v42, -v38, v41, v40
	v_fmac_f32_e32 v41, v42, v39
	v_fma_f32 v38, -v38, v41, v40
	v_div_fmas_f32 v38, v38, v39, v41
	v_div_fixup_f32 v36, v38, v37, v36
	v_mul_f32_e32 v30, v36, v30
	v_and_b32_e32 v36, 0xffff0000, v89
	v_mul_f32_e32 v31, v31, v36
	v_and_b32_e32 v36, 0xffff0000, v87
	v_mul_f32_e32 v37, 0xbfb8aa3b, v36
	v_exp_f32_e32 v37, v37
	s_nop 0
	v_add_f32_e32 v37, 1.0, v37
	v_div_scale_f32 v38, s[2:3], v37, v37, v36
	v_rcp_f32_e32 v39, v38
	s_nop 0
	v_fma_f32 v40, -v38, v39, 1.0
	v_fmac_f32_e32 v39, v40, v39
	v_div_scale_f32 v40, vcc, v36, v37, v36
	v_mul_f32_e32 v41, v40, v39
	v_fma_f32 v42, -v38, v41, v40
	v_fmac_f32_e32 v41, v42, v39
	v_fma_f32 v38, -v38, v41, v40
	v_div_fmas_f32 v38, v38, v39, v41
	v_div_fixup_f32 v36, v38, v37, v36
	v_mul_f32_e32 v31, v36, v31
	v_mul_f32_e32 v36, v29, v29
	v_mul_f32_e32 v37, v31, v31
	v_fmac_f32_e32 v36, v28, v28
	v_fmac_f32_e32 v37, v30, v30
	v_cvt_pk_bf16_f32 v28, v28, v29
	v_cvt_pk_bf16_f32 v29, v30, v31
	v_add_co_u32_e32 v30, vcc, s1, v34
	v_add_f32_e32 v36, v36, v37
	s_nop 0
	v_addc_co_u32_e32 v31, vcc, 0, v35, vcc
	global_store_dwordx2 v[30:31], v[28:29], off offset:2048
	v_lshlrev_b32_e32 v28, 16, v84
	v_mul_f32_e32 v24, v24, v28
	v_lshlrev_b32_e32 v28, 16, v82
	v_mul_f32_e32 v29, 0xbfb8aa3b, v28
	v_exp_f32_e32 v29, v29
	s_nop 0
	v_add_f32_e32 v29, 1.0, v29
	v_div_scale_f32 v30, s[2:3], v29, v29, v28
	v_rcp_f32_e32 v31, v30
	s_nop 0
	v_fma_f32 v34, -v30, v31, 1.0
	v_fmac_f32_e32 v31, v34, v31
	v_div_scale_f32 v34, vcc, v28, v29, v28
	v_mul_f32_e32 v35, v34, v31
	v_fma_f32 v37, -v30, v35, v34
	v_fmac_f32_e32 v35, v37, v31
	v_fma_f32 v30, -v30, v35, v34
	v_div_fmas_f32 v30, v30, v31, v35
	v_div_fixup_f32 v28, v30, v29, v28
	v_mul_f32_e32 v24, v28, v24
	v_and_b32_e32 v28, 0xffff0000, v84
	v_mul_f32_e32 v25, v25, v28
	v_and_b32_e32 v28, 0xffff0000, v82
	v_mul_f32_e32 v29, 0xbfb8aa3b, v28
	v_exp_f32_e32 v29, v29
	s_nop 0
	v_add_f32_e32 v29, 1.0, v29
	v_div_scale_f32 v30, s[2:3], v29, v29, v28
	v_rcp_f32_e32 v31, v30
	s_nop 0
	v_fma_f32 v34, -v30, v31, 1.0
	v_fmac_f32_e32 v31, v34, v31
	v_div_scale_f32 v34, vcc, v28, v29, v28
	v_mul_f32_e32 v35, v34, v31
	v_fma_f32 v37, -v30, v35, v34
	v_fmac_f32_e32 v35, v37, v31
	v_fma_f32 v30, -v30, v35, v34
	v_div_fmas_f32 v30, v30, v31, v35
	v_div_fixup_f32 v28, v30, v29, v28
	v_mul_f32_e32 v25, v28, v25
	v_lshlrev_b32_e32 v28, 16, v85
	v_mul_f32_e32 v26, v26, v28
	v_lshlrev_b32_e32 v28, 16, v83
	v_mul_f32_e32 v29, 0xbfb8aa3b, v28
	v_exp_f32_e32 v29, v29
	s_nop 0
	v_add_f32_e32 v29, 1.0, v29
	v_div_scale_f32 v30, s[2:3], v29, v29, v28
	v_rcp_f32_e32 v31, v30
	s_nop 0
	v_fma_f32 v34, -v30, v31, 1.0
	v_fmac_f32_e32 v31, v34, v31
	v_div_scale_f32 v34, vcc, v28, v29, v28
	v_mul_f32_e32 v35, v34, v31
	v_fma_f32 v37, -v30, v35, v34
	v_fmac_f32_e32 v35, v37, v31
	v_fma_f32 v30, -v30, v35, v34
	v_div_fmas_f32 v30, v30, v31, v35
	v_div_fixup_f32 v28, v30, v29, v28
	v_mul_f32_e32 v26, v28, v26
	v_and_b32_e32 v28, 0xffff0000, v85
	v_mul_f32_e32 v27, v27, v28
	v_and_b32_e32 v28, 0xffff0000, v83
	v_mul_f32_e32 v29, 0xbfb8aa3b, v28
	v_exp_f32_e32 v29, v29
	s_nop 0
	v_add_f32_e32 v29, 1.0, v29
	v_div_scale_f32 v30, s[2:3], v29, v29, v28
	v_rcp_f32_e32 v31, v30
	s_nop 0
	v_fma_f32 v34, -v30, v31, 1.0
	v_fmac_f32_e32 v31, v34, v31
	v_div_scale_f32 v34, vcc, v28, v29, v28
	v_mul_f32_e32 v35, v34, v31
	v_fma_f32 v37, -v30, v35, v34
	v_fmac_f32_e32 v35, v37, v31
	v_fma_f32 v30, -v30, v35, v34
	v_div_fmas_f32 v30, v30, v31, v35
	v_div_fixup_f32 v28, v30, v29, v28
	v_mul_f32_e32 v27, v28, v27
	v_mul_f32_e32 v28, v25, v25
	v_fmac_f32_e32 v28, v24, v24
	v_cvt_pk_bf16_f32 v24, v24, v25
	v_cvt_pk_bf16_f32 v25, v26, v27
	global_store_dwordx2 v[32:33], v[24:25], off offset:32
	v_lshlrev_b32_e32 v24, 16, v80
	v_mul_f32_e32 v20, v20, v24
	v_lshlrev_b32_e32 v24, 16, v78
	v_mul_f32_e32 v25, 0xbfb8aa3b, v24
	v_exp_f32_e32 v25, v25
	v_mul_f32_e32 v29, v27, v27
	v_fmac_f32_e32 v29, v26, v26
	v_add_f32_e32 v28, v28, v29
	v_add_f32_e32 v25, 1.0, v25
	v_div_scale_f32 v26, s[2:3], v25, v25, v24
	v_rcp_f32_e32 v27, v26
	v_add_f32_e32 v28, v36, v28
	v_fma_f32 v29, -v26, v27, 1.0
	v_fmac_f32_e32 v27, v29, v27
	v_div_scale_f32 v29, vcc, v24, v25, v24
	v_mul_f32_e32 v30, v29, v27
	v_fma_f32 v31, -v26, v30, v29
	v_fmac_f32_e32 v30, v31, v27
	v_fma_f32 v26, -v26, v30, v29
	v_div_fmas_f32 v26, v26, v27, v30
	v_div_fixup_f32 v24, v26, v25, v24
	v_mul_f32_e32 v20, v24, v20
	v_and_b32_e32 v24, 0xffff0000, v80
	v_mul_f32_e32 v21, v21, v24
	v_and_b32_e32 v24, 0xffff0000, v78
	v_mul_f32_e32 v25, 0xbfb8aa3b, v24
	v_exp_f32_e32 v25, v25
	s_nop 0
	v_add_f32_e32 v25, 1.0, v25
	v_div_scale_f32 v26, s[2:3], v25, v25, v24
	v_rcp_f32_e32 v27, v26
	s_nop 0
	v_fma_f32 v29, -v26, v27, 1.0
	v_fmac_f32_e32 v27, v29, v27
	v_div_scale_f32 v29, vcc, v24, v25, v24
	v_mul_f32_e32 v30, v29, v27
	v_fma_f32 v31, -v26, v30, v29
	v_fmac_f32_e32 v30, v31, v27
	v_fma_f32 v26, -v26, v30, v29
	v_div_fmas_f32 v26, v26, v27, v30
	v_div_fixup_f32 v24, v26, v25, v24
	v_mul_f32_e32 v21, v24, v21
	v_lshlrev_b32_e32 v24, 16, v81
	v_mul_f32_e32 v22, v22, v24
	v_lshlrev_b32_e32 v24, 16, v79
	v_mul_f32_e32 v25, 0xbfb8aa3b, v24
	v_exp_f32_e32 v25, v25
	s_nop 0
	v_add_f32_e32 v25, 1.0, v25
	v_div_scale_f32 v26, s[2:3], v25, v25, v24
	v_rcp_f32_e32 v27, v26
	s_nop 0
	v_fma_f32 v29, -v26, v27, 1.0
	v_fmac_f32_e32 v27, v29, v27
	v_div_scale_f32 v29, vcc, v24, v25, v24
	v_mul_f32_e32 v30, v29, v27
	v_fma_f32 v31, -v26, v30, v29
	v_fmac_f32_e32 v30, v31, v27
	v_fma_f32 v26, -v26, v30, v29
	v_div_fmas_f32 v26, v26, v27, v30
	v_div_fixup_f32 v24, v26, v25, v24
	v_mul_f32_e32 v22, v24, v22
	v_and_b32_e32 v24, 0xffff0000, v81
	v_mul_f32_e32 v23, v23, v24
	v_and_b32_e32 v24, 0xffff0000, v79
	v_mul_f32_e32 v25, 0xbfb8aa3b, v24
	v_exp_f32_e32 v25, v25
	s_nop 0
	v_add_f32_e32 v25, 1.0, v25
	v_div_scale_f32 v26, s[2:3], v25, v25, v24
	v_rcp_f32_e32 v27, v26
	s_nop 0
	v_fma_f32 v29, -v26, v27, 1.0
	v_fmac_f32_e32 v27, v29, v27
	v_div_scale_f32 v29, vcc, v24, v25, v24
	v_mul_f32_e32 v30, v29, v27
	v_fma_f32 v31, -v26, v30, v29
	v_fmac_f32_e32 v30, v31, v27
	v_fma_f32 v26, -v26, v30, v29
	v_div_fmas_f32 v26, v26, v27, v30
	v_div_fixup_f32 v24, v26, v25, v24
	v_mul_f32_e32 v23, v24, v23
	v_mul_f32_e32 v24, v21, v21
	v_fmac_f32_e32 v24, v20, v20
	v_cvt_pk_bf16_f32 v20, v20, v21
	v_cvt_pk_bf16_f32 v21, v22, v23
	global_store_dwordx2 v[32:33], v[20:21], off offset:64
	v_lshlrev_b32_e32 v20, 16, v76
	v_mul_f32_e32 v16, v16, v20
	v_lshlrev_b32_e32 v20, 16, v74
	v_mul_f32_e32 v21, 0xbfb8aa3b, v20
	v_exp_f32_e32 v21, v21
	v_mul_f32_e32 v25, v23, v23
	v_fmac_f32_e32 v25, v22, v22
	v_add_f32_e32 v24, v24, v25
	v_add_f32_e32 v21, 1.0, v21
	v_div_scale_f32 v22, s[2:3], v21, v21, v20
	v_rcp_f32_e32 v23, v22
	v_add_f32_e32 v24, v28, v24
	v_fma_f32 v25, -v22, v23, 1.0
	v_fmac_f32_e32 v23, v25, v23
	v_div_scale_f32 v25, vcc, v20, v21, v20
	v_mul_f32_e32 v26, v25, v23
	v_fma_f32 v27, -v22, v26, v25
	v_fmac_f32_e32 v26, v27, v23
	v_fma_f32 v22, -v22, v26, v25
	v_div_fmas_f32 v22, v22, v23, v26
	v_div_fixup_f32 v20, v22, v21, v20
	v_mul_f32_e32 v16, v20, v16
	v_and_b32_e32 v20, 0xffff0000, v76
	v_mul_f32_e32 v17, v17, v20
	v_and_b32_e32 v20, 0xffff0000, v74
	v_mul_f32_e32 v21, 0xbfb8aa3b, v20
	v_exp_f32_e32 v21, v21
	s_nop 0
	v_add_f32_e32 v21, 1.0, v21
	v_div_scale_f32 v22, s[2:3], v21, v21, v20
	v_rcp_f32_e32 v23, v22
	s_nop 0
	v_fma_f32 v25, -v22, v23, 1.0
	v_fmac_f32_e32 v23, v25, v23
	v_div_scale_f32 v25, vcc, v20, v21, v20
	v_mul_f32_e32 v26, v25, v23
	v_fma_f32 v27, -v22, v26, v25
	v_fmac_f32_e32 v26, v27, v23
	v_fma_f32 v22, -v22, v26, v25
	v_div_fmas_f32 v22, v22, v23, v26
	v_div_fixup_f32 v20, v22, v21, v20
	v_mul_f32_e32 v17, v20, v17
	v_lshlrev_b32_e32 v20, 16, v77
	v_mul_f32_e32 v18, v18, v20
	v_lshlrev_b32_e32 v20, 16, v75
	v_mul_f32_e32 v21, 0xbfb8aa3b, v20
	v_exp_f32_e32 v21, v21
	s_nop 0
	v_add_f32_e32 v21, 1.0, v21
	v_div_scale_f32 v22, s[2:3], v21, v21, v20
	v_rcp_f32_e32 v23, v22
	s_nop 0
	v_fma_f32 v25, -v22, v23, 1.0
	v_fmac_f32_e32 v23, v25, v23
	v_div_scale_f32 v25, vcc, v20, v21, v20
	v_mul_f32_e32 v26, v25, v23
	v_fma_f32 v27, -v22, v26, v25
	v_fmac_f32_e32 v26, v27, v23
	v_fma_f32 v22, -v22, v26, v25
	v_div_fmas_f32 v22, v22, v23, v26
	v_div_fixup_f32 v20, v22, v21, v20
	v_mul_f32_e32 v18, v20, v18
	v_and_b32_e32 v20, 0xffff0000, v77
	v_mul_f32_e32 v19, v19, v20
	v_and_b32_e32 v20, 0xffff0000, v75
	v_mul_f32_e32 v21, 0xbfb8aa3b, v20
	v_exp_f32_e32 v21, v21
	s_nop 0
	v_add_f32_e32 v21, 1.0, v21
	v_div_scale_f32 v22, s[2:3], v21, v21, v20
	v_rcp_f32_e32 v23, v22
	s_nop 0
	v_fma_f32 v25, -v22, v23, 1.0
	v_fmac_f32_e32 v23, v25, v23
	v_div_scale_f32 v25, vcc, v20, v21, v20
	v_mul_f32_e32 v26, v25, v23
	v_fma_f32 v27, -v22, v26, v25
	v_fmac_f32_e32 v26, v27, v23
	v_fma_f32 v22, -v22, v26, v25
	v_div_fmas_f32 v22, v22, v23, v26
	v_div_fixup_f32 v20, v22, v21, v20
	v_mul_f32_e32 v19, v20, v19
	v_mul_f32_e32 v20, v17, v17
	v_fmac_f32_e32 v20, v16, v16
	v_cvt_pk_bf16_f32 v16, v16, v17
	v_cvt_pk_bf16_f32 v17, v18, v19
	global_store_dwordx2 v[32:33], v[16:17], off offset:96
	v_lshlrev_b32_e32 v16, 16, v72
	v_mul_f32_e32 v12, v12, v16
	v_lshlrev_b32_e32 v16, 16, v70
	v_mul_f32_e32 v17, 0xbfb8aa3b, v16
	v_exp_f32_e32 v17, v17
	v_mul_f32_e32 v21, v19, v19
	v_fmac_f32_e32 v21, v18, v18
	v_add_f32_e32 v20, v20, v21
	v_add_f32_e32 v17, 1.0, v17
	v_div_scale_f32 v18, s[2:3], v17, v17, v16
	v_rcp_f32_e32 v19, v18
	v_add_f32_e32 v20, v24, v20
	v_fma_f32 v21, -v18, v19, 1.0
	v_fmac_f32_e32 v19, v21, v19
	v_div_scale_f32 v21, vcc, v16, v17, v16
	v_mul_f32_e32 v22, v21, v19
	v_fma_f32 v23, -v18, v22, v21
	v_fmac_f32_e32 v22, v23, v19
	v_fma_f32 v18, -v18, v22, v21
	v_div_fmas_f32 v18, v18, v19, v22
	v_div_fixup_f32 v16, v18, v17, v16
	v_mul_f32_e32 v12, v16, v12
	v_and_b32_e32 v16, 0xffff0000, v72
	v_mul_f32_e32 v13, v13, v16
	v_and_b32_e32 v16, 0xffff0000, v70
	v_mul_f32_e32 v17, 0xbfb8aa3b, v16
	v_exp_f32_e32 v17, v17
	s_nop 0
	v_add_f32_e32 v17, 1.0, v17
	v_div_scale_f32 v18, s[2:3], v17, v17, v16
	v_rcp_f32_e32 v19, v18
	s_nop 0
	v_fma_f32 v21, -v18, v19, 1.0
	v_fmac_f32_e32 v19, v21, v19
	v_div_scale_f32 v21, vcc, v16, v17, v16
	v_mul_f32_e32 v22, v21, v19
	v_fma_f32 v23, -v18, v22, v21
	v_fmac_f32_e32 v22, v23, v19
	v_fma_f32 v18, -v18, v22, v21
	v_div_fmas_f32 v18, v18, v19, v22
	v_div_fixup_f32 v16, v18, v17, v16
	v_mul_f32_e32 v13, v16, v13
	v_lshlrev_b32_e32 v16, 16, v73
	v_mul_f32_e32 v14, v14, v16
	v_lshlrev_b32_e32 v16, 16, v71
	v_mul_f32_e32 v17, 0xbfb8aa3b, v16
	v_exp_f32_e32 v17, v17
	s_nop 0
	v_add_f32_e32 v17, 1.0, v17
	v_div_scale_f32 v18, s[2:3], v17, v17, v16
	v_rcp_f32_e32 v19, v18
	s_nop 0
	v_fma_f32 v21, -v18, v19, 1.0
	v_fmac_f32_e32 v19, v21, v19
	v_div_scale_f32 v21, vcc, v16, v17, v16
	v_mul_f32_e32 v22, v21, v19
	v_fma_f32 v23, -v18, v22, v21
	v_fmac_f32_e32 v22, v23, v19
	v_fma_f32 v18, -v18, v22, v21
	v_div_fmas_f32 v18, v18, v19, v22
	v_div_fixup_f32 v16, v18, v17, v16
	v_mul_f32_e32 v14, v16, v14
	v_and_b32_e32 v16, 0xffff0000, v73
	v_mul_f32_e32 v15, v15, v16
	v_and_b32_e32 v16, 0xffff0000, v71
	v_mul_f32_e32 v17, 0xbfb8aa3b, v16
	v_exp_f32_e32 v17, v17
	s_nop 0
	v_add_f32_e32 v17, 1.0, v17
	v_div_scale_f32 v18, s[2:3], v17, v17, v16
	v_rcp_f32_e32 v19, v18
	s_nop 0
	v_fma_f32 v21, -v18, v19, 1.0
	v_fmac_f32_e32 v19, v21, v19
	v_div_scale_f32 v21, vcc, v16, v17, v16
	v_mul_f32_e32 v22, v21, v19
	v_fma_f32 v23, -v18, v22, v21
	v_fmac_f32_e32 v22, v23, v19
	v_fma_f32 v18, -v18, v22, v21
	v_div_fmas_f32 v18, v18, v19, v22
	v_div_fixup_f32 v16, v18, v17, v16
	v_mul_f32_e32 v15, v16, v15
	v_mul_f32_e32 v16, v13, v13
	v_fmac_f32_e32 v16, v12, v12
	v_cvt_pk_bf16_f32 v12, v12, v13
	v_cvt_pk_bf16_f32 v13, v14, v15
	global_store_dwordx2 v[32:33], v[12:13], off offset:128
	v_lshlrev_b32_e32 v12, 16, v68
	v_mul_f32_e32 v8, v8, v12
	v_lshlrev_b32_e32 v12, 16, v66
	v_mul_f32_e32 v13, 0xbfb8aa3b, v12
	v_exp_f32_e32 v13, v13
	v_mul_f32_e32 v17, v15, v15
	v_fmac_f32_e32 v17, v14, v14
	v_add_f32_e32 v16, v16, v17
	v_add_f32_e32 v13, 1.0, v13
	v_div_scale_f32 v14, s[2:3], v13, v13, v12
	v_rcp_f32_e32 v15, v14
	v_add_f32_e32 v16, v20, v16
	v_fma_f32 v17, -v14, v15, 1.0
	v_fmac_f32_e32 v15, v17, v15
	v_div_scale_f32 v17, vcc, v12, v13, v12
	v_mul_f32_e32 v18, v17, v15
	v_fma_f32 v19, -v14, v18, v17
	v_fmac_f32_e32 v18, v19, v15
	v_fma_f32 v14, -v14, v18, v17
	v_div_fmas_f32 v14, v14, v15, v18
	v_div_fixup_f32 v12, v14, v13, v12
	v_mul_f32_e32 v8, v12, v8
	v_and_b32_e32 v12, 0xffff0000, v68
	v_mul_f32_e32 v9, v9, v12
	v_and_b32_e32 v12, 0xffff0000, v66
	v_mul_f32_e32 v13, 0xbfb8aa3b, v12
	v_exp_f32_e32 v13, v13
	s_nop 0
	v_add_f32_e32 v13, 1.0, v13
	v_div_scale_f32 v14, s[2:3], v13, v13, v12
	v_rcp_f32_e32 v15, v14
	s_nop 0
	v_fma_f32 v17, -v14, v15, 1.0
	v_fmac_f32_e32 v15, v17, v15
	v_div_scale_f32 v17, vcc, v12, v13, v12
	v_mul_f32_e32 v18, v17, v15
	v_fma_f32 v19, -v14, v18, v17
	v_fmac_f32_e32 v18, v19, v15
	v_fma_f32 v14, -v14, v18, v17
	v_div_fmas_f32 v14, v14, v15, v18
	v_div_fixup_f32 v12, v14, v13, v12
	v_mul_f32_e32 v9, v12, v9
	v_lshlrev_b32_e32 v12, 16, v69
	v_mul_f32_e32 v10, v10, v12
	v_lshlrev_b32_e32 v12, 16, v67
	v_mul_f32_e32 v13, 0xbfb8aa3b, v12
	v_exp_f32_e32 v13, v13
	s_nop 0
	v_add_f32_e32 v13, 1.0, v13
	v_div_scale_f32 v14, s[2:3], v13, v13, v12
	v_rcp_f32_e32 v15, v14
	s_nop 0
	v_fma_f32 v17, -v14, v15, 1.0
	v_fmac_f32_e32 v15, v17, v15
	v_div_scale_f32 v17, vcc, v12, v13, v12
	v_mul_f32_e32 v18, v17, v15
	v_fma_f32 v19, -v14, v18, v17
	v_fmac_f32_e32 v18, v19, v15
	v_fma_f32 v14, -v14, v18, v17
	v_div_fmas_f32 v14, v14, v15, v18
	v_div_fixup_f32 v12, v14, v13, v12
	v_mul_f32_e32 v10, v12, v10
	v_and_b32_e32 v12, 0xffff0000, v69
	v_mul_f32_e32 v11, v11, v12
	v_and_b32_e32 v12, 0xffff0000, v67
	v_mul_f32_e32 v13, 0xbfb8aa3b, v12
	v_exp_f32_e32 v13, v13
	s_nop 0
	v_add_f32_e32 v13, 1.0, v13
	v_div_scale_f32 v14, s[2:3], v13, v13, v12
	v_rcp_f32_e32 v15, v14
	s_nop 0
	v_fma_f32 v17, -v14, v15, 1.0
	v_fmac_f32_e32 v15, v17, v15
	v_div_scale_f32 v17, vcc, v12, v13, v12
	v_mul_f32_e32 v18, v17, v15
	v_fma_f32 v19, -v14, v18, v17
	v_fmac_f32_e32 v18, v19, v15
	v_fma_f32 v14, -v14, v18, v17
	v_div_fmas_f32 v14, v14, v15, v18
	v_div_fixup_f32 v12, v14, v13, v12
	v_mul_f32_e32 v11, v12, v11
	v_mul_f32_e32 v12, v9, v9
	v_fmac_f32_e32 v12, v8, v8
	v_cvt_pk_bf16_f32 v8, v8, v9
	v_cvt_pk_bf16_f32 v9, v10, v11
	global_store_dwordx2 v[32:33], v[8:9], off offset:160
	v_lshlrev_b32_e32 v8, 16, v64
	v_mul_f32_e32 v4, v4, v8
	v_lshlrev_b32_e32 v8, 16, v62
	v_mul_f32_e32 v9, 0xbfb8aa3b, v8
	v_exp_f32_e32 v9, v9
	v_mul_f32_e32 v13, v11, v11
	v_fmac_f32_e32 v13, v10, v10
	v_add_f32_e32 v12, v12, v13
	v_add_f32_e32 v9, 1.0, v9
	v_div_scale_f32 v10, s[2:3], v9, v9, v8
	v_rcp_f32_e32 v11, v10
	v_add_f32_e32 v12, v16, v12
	v_fma_f32 v13, -v10, v11, 1.0
	v_fmac_f32_e32 v11, v13, v11
	v_div_scale_f32 v13, vcc, v8, v9, v8
	v_mul_f32_e32 v14, v13, v11
	v_fma_f32 v15, -v10, v14, v13
	v_fmac_f32_e32 v14, v15, v11
	v_fma_f32 v10, -v10, v14, v13
	v_div_fmas_f32 v10, v10, v11, v14
	v_div_fixup_f32 v8, v10, v9, v8
	v_mul_f32_e32 v4, v8, v4
	v_and_b32_e32 v8, 0xffff0000, v64
	v_mul_f32_e32 v5, v5, v8
	v_and_b32_e32 v8, 0xffff0000, v62
	v_mul_f32_e32 v9, 0xbfb8aa3b, v8
	v_exp_f32_e32 v9, v9
	s_nop 0
	v_add_f32_e32 v9, 1.0, v9
	v_div_scale_f32 v10, s[2:3], v9, v9, v8
	v_rcp_f32_e32 v11, v10
	s_nop 0
	v_fma_f32 v13, -v10, v11, 1.0
	v_fmac_f32_e32 v11, v13, v11
	v_div_scale_f32 v13, vcc, v8, v9, v8
	v_mul_f32_e32 v14, v13, v11
	v_fma_f32 v15, -v10, v14, v13
	v_fmac_f32_e32 v14, v15, v11
	v_fma_f32 v10, -v10, v14, v13
	v_div_fmas_f32 v10, v10, v11, v14
	v_div_fixup_f32 v8, v10, v9, v8
	v_mul_f32_e32 v5, v8, v5
	v_lshlrev_b32_e32 v8, 16, v65
	v_mul_f32_e32 v6, v6, v8
	v_lshlrev_b32_e32 v8, 16, v63
	v_mul_f32_e32 v9, 0xbfb8aa3b, v8
	v_exp_f32_e32 v9, v9
	s_nop 0
	v_add_f32_e32 v9, 1.0, v9
	v_div_scale_f32 v10, s[2:3], v9, v9, v8
	v_rcp_f32_e32 v11, v10
	s_nop 0
	v_fma_f32 v13, -v10, v11, 1.0
	v_fmac_f32_e32 v11, v13, v11
	v_div_scale_f32 v13, vcc, v8, v9, v8
	v_mul_f32_e32 v14, v13, v11
	v_fma_f32 v15, -v10, v14, v13
	v_fmac_f32_e32 v14, v15, v11
	v_fma_f32 v10, -v10, v14, v13
	v_div_fmas_f32 v10, v10, v11, v14
	v_div_fixup_f32 v8, v10, v9, v8
	v_mul_f32_e32 v6, v8, v6
	v_and_b32_e32 v8, 0xffff0000, v65
	v_mul_f32_e32 v7, v7, v8
	v_and_b32_e32 v8, 0xffff0000, v63
	v_mul_f32_e32 v9, 0xbfb8aa3b, v8
	v_exp_f32_e32 v9, v9
	s_nop 0
	v_add_f32_e32 v9, 1.0, v9
	v_div_scale_f32 v10, s[2:3], v9, v9, v8
	v_rcp_f32_e32 v11, v10
	s_nop 0
	v_fma_f32 v13, -v10, v11, 1.0
	v_fmac_f32_e32 v11, v13, v11
	v_div_scale_f32 v13, vcc, v8, v9, v8
	v_mul_f32_e32 v14, v13, v11
	v_fma_f32 v15, -v10, v14, v13
	v_fmac_f32_e32 v14, v15, v11
	v_fma_f32 v10, -v10, v14, v13
	v_div_fmas_f32 v10, v10, v11, v14
	v_div_fixup_f32 v8, v10, v9, v8
	v_mul_f32_e32 v7, v8, v7
	v_mul_f32_e32 v8, v5, v5
	v_fmac_f32_e32 v8, v4, v4
	v_cvt_pk_bf16_f32 v4, v4, v5
	v_cvt_pk_bf16_f32 v5, v6, v7
	global_store_dwordx2 v[32:33], v[4:5], off offset:192
	v_lshlrev_b32_e32 v4, 16, v60
	v_mul_f32_e32 v0, v0, v4
	v_lshlrev_b32_e32 v4, 16, v58
	v_mul_f32_e32 v5, 0xbfb8aa3b, v4
	v_exp_f32_e32 v5, v5
	v_mul_f32_e32 v9, v7, v7
	v_fmac_f32_e32 v9, v6, v6
	v_add_f32_e32 v8, v8, v9
	v_add_f32_e32 v5, 1.0, v5
	v_div_scale_f32 v6, s[2:3], v5, v5, v4
	v_rcp_f32_e32 v7, v6
	v_add_f32_e32 v8, v12, v8
	v_fma_f32 v9, -v6, v7, 1.0
	v_fmac_f32_e32 v7, v9, v7
	v_div_scale_f32 v9, vcc, v4, v5, v4
	v_mul_f32_e32 v10, v9, v7
	v_fma_f32 v11, -v6, v10, v9
	v_fmac_f32_e32 v10, v11, v7
	v_fma_f32 v6, -v6, v10, v9
	v_div_fmas_f32 v6, v6, v7, v10
	v_div_fixup_f32 v4, v6, v5, v4
	v_mul_f32_e32 v0, v4, v0
	v_and_b32_e32 v4, 0xffff0000, v60
	v_mul_f32_e32 v1, v1, v4
	v_and_b32_e32 v4, 0xffff0000, v58
	v_mul_f32_e32 v5, 0xbfb8aa3b, v4
	v_exp_f32_e32 v5, v5
	s_nop 0
	v_add_f32_e32 v5, 1.0, v5
	v_div_scale_f32 v6, s[2:3], v5, v5, v4
	v_rcp_f32_e32 v7, v6
	s_nop 0
	v_fma_f32 v9, -v6, v7, 1.0
	v_fmac_f32_e32 v7, v9, v7
	v_div_scale_f32 v9, vcc, v4, v5, v4
	v_mul_f32_e32 v10, v9, v7
	v_fma_f32 v11, -v6, v10, v9
	v_fmac_f32_e32 v10, v11, v7
	v_fma_f32 v6, -v6, v10, v9
	v_div_fmas_f32 v6, v6, v7, v10
	v_div_fixup_f32 v4, v6, v5, v4
	v_mul_f32_e32 v1, v4, v1
	v_lshlrev_b32_e32 v4, 16, v61
	v_mul_f32_e32 v2, v2, v4
	v_lshlrev_b32_e32 v4, 16, v59
	v_mul_f32_e32 v5, 0xbfb8aa3b, v4
	v_exp_f32_e32 v5, v5
	s_nop 0
	v_add_f32_e32 v5, 1.0, v5
	v_div_scale_f32 v6, s[2:3], v5, v5, v4
	v_rcp_f32_e32 v7, v6
	s_nop 0
	v_fma_f32 v9, -v6, v7, 1.0
	v_fmac_f32_e32 v7, v9, v7
	v_div_scale_f32 v9, vcc, v4, v5, v4
	v_mul_f32_e32 v10, v9, v7
	v_fma_f32 v11, -v6, v10, v9
	v_fmac_f32_e32 v10, v11, v7
	v_fma_f32 v6, -v6, v10, v9
	v_div_fmas_f32 v6, v6, v7, v10
	v_div_fixup_f32 v4, v6, v5, v4
	v_mul_f32_e32 v2, v4, v2
	v_and_b32_e32 v4, 0xffff0000, v61
	v_mul_f32_e32 v3, v3, v4
	v_and_b32_e32 v4, 0xffff0000, v59
	v_mul_f32_e32 v5, 0xbfb8aa3b, v4
	v_exp_f32_e32 v5, v5
	s_nop 0
	v_add_f32_e32 v5, 1.0, v5
	v_div_scale_f32 v6, s[2:3], v5, v5, v4
	v_rcp_f32_e32 v7, v6
	s_nop 0
	v_fma_f32 v9, -v6, v7, 1.0
	v_fmac_f32_e32 v7, v9, v7
	v_div_scale_f32 v9, vcc, v4, v5, v4
	v_mul_f32_e32 v10, v9, v7
	v_fma_f32 v11, -v6, v10, v9
	v_fmac_f32_e32 v10, v11, v7
	v_fma_f32 v6, -v6, v10, v9
	v_div_fmas_f32 v6, v6, v7, v10
	v_div_fixup_f32 v4, v6, v5, v4
	v_mul_f32_e32 v3, v4, v3
	v_mul_f32_e32 v4, v1, v1
	v_mul_f32_e32 v5, v3, v3
	v_fmac_f32_e32 v4, v0, v0
	v_fmac_f32_e32 v5, v2, v2
	v_add_f32_e32 v4, v4, v5
	v_add_f32_e32 v4, v8, v4
	v_cvt_pk_bf16_f32 v0, v0, v1
	v_cvt_pk_bf16_f32 v1, v2, v3
	global_store_dwordx2 v[32:33], v[0:1], off offset:224
	ds_bpermute_b32 v0, v109, v4
	s_waitcnt lgkmcnt(0)
	v_add_f32_e32 v0, v4, v0
	ds_bpermute_b32 v1, v108, v0
	s_and_saveexec_b64 s[44:45], s[40:41]
	s_cbranch_execz .LBB0_248
	s_waitcnt lgkmcnt(0)
	v_add_f32_e32 v2, v0, v1
	v_lshl_add_u64 v[0:1], v[56:57], 4, s[46:47]
	s_lshl_b32 s34, s73, 2
	v_lshl_add_u64 v[0:1], v[0:1], 0, s[34:35]
	global_store_dword v[0:1], v2, off
	s_branch .LBB0_248
